# v17 + P0/P2a weight-conversion loops: the 32 per-k gain loads of an item issued together instead of one load + vmcnt(0) per element
# speedup vs baseline: 1.0115x; 1.0097x over previous
; __device__ __forceinline__ void conv_matrix(const float* W, int K, int N, bf16* WT, const float* sk, const float* sn, int mode, LAS float* scr, int lane, int gw, int NGW) {
;     ...
;     for (; it < nitems; it += NGW) {
;         const int kb = it / nblk, nb = it - kb * nblk, n0 = 32 * nb, k0 = 64 * kb; int drow0 = n0;
;         if (mode == 1) drow0 = n0 < DFF ? 256 * (n0 >> 7) + (n0 & 127) : 256 * ((n0 - DFF) >> 7) + 128 + ((n0 - DFF) & 127);
; #pragma unroll
;         for (int i = 0; i < 32; ++i) { const int kk = 2 * i + (lane >> 5); float t = v[i]; if (sk) t *= sk[k0 + kk]; scr[kk * 33 + (lane & 31)] = t; }
.LBB0_11:
	s_mul_hi_i32 s0, s80, 0x4ec4ec4f
	s_lshr_b32 s1, s0, 31
	s_ashr_i32 s81, s0, 7
	s_add_i32 s81, s81, s1
	s_lshl_b32 s0, s81, 6
	s_and_b64 vcc, exec, s[4:5]
	s_cbranch_vccnz .Lgn_skip_0
	s_ashr_i32 s1, s0, 31
	v_lshl_add_u64 v[92:93], s[0:1], 0, v[36:37]
	v_lshl_add_u64 v[92:93], v[92:93], 2, s[38:39]
	global_load_dword v94, v[92:93], off
	global_load_dword v95, v[92:93], off offset:8
	global_load_dword v96, v[92:93], off offset:16
	global_load_dword v97, v[92:93], off offset:24
	global_load_dword v98, v[92:93], off offset:32
	global_load_dword v99, v[92:93], off offset:40
	global_load_dword v100, v[92:93], off offset:48
	global_load_dword v101, v[92:93], off offset:56
	global_load_dword v102, v[92:93], off offset:64
	global_load_dword v103, v[92:93], off offset:72
	global_load_dword v104, v[92:93], off offset:80
	global_load_dword v105, v[92:93], off offset:88
	global_load_dword v106, v[92:93], off offset:96
	global_load_dword v107, v[92:93], off offset:104
	global_load_dword v108, v[92:93], off offset:112
	global_load_dword v109, v[92:93], off offset:120
	global_load_dword v110, v[92:93], off offset:128
	global_load_dword v111, v[92:93], off offset:136
	global_load_dword v112, v[92:93], off offset:144
	global_load_dword v113, v[92:93], off offset:152
	global_load_dword v114, v[92:93], off offset:160
	global_load_dword v115, v[92:93], off offset:168
	global_load_dword v116, v[92:93], off offset:176
	global_load_dword v117, v[92:93], off offset:184
	global_load_dword v118, v[92:93], off offset:192
	global_load_dword v119, v[92:93], off offset:200
	global_load_dword v120, v[92:93], off offset:208
	global_load_dword v121, v[92:93], off offset:216
	global_load_dword v122, v[92:93], off offset:224
	global_load_dword v123, v[92:93], off offset:232
	global_load_dword v124, v[92:93], off offset:240
	global_load_dword v125, v[92:93], off offset:248
.Lgn_skip_0:
	s_and_b64 vcc, exec, s[4:5]
	s_waitcnt vmcnt(31)
	v_mov_b32_e32 v48, v2
	s_cbranch_vccnz .LBB0_13
	v_mul_f32_e32 v48, v2, v94
.LBB0_13:
	ds_write_b32 v46, v48
	s_and_b64 vcc, exec, s[4:5]
	s_waitcnt vmcnt(30)
	v_mov_b32_e32 v48, v1
	s_cbranch_vccnz .LBB0_15
	v_mul_f32_e32 v48, v1, v95
.LBB0_15:
	ds_write_b32 v46, v48 offset:264
	s_and_b64 vcc, exec, s[4:5]
	s_waitcnt vmcnt(29)
	v_mov_b32_e32 v48, v4
	s_cbranch_vccnz .LBB0_17
	v_mul_f32_e32 v48, v4, v96
.LBB0_17:
	ds_write_b32 v46, v48 offset:528
	s_and_b64 vcc, exec, s[4:5]
	s_waitcnt vmcnt(28)
	v_mov_b32_e32 v48, v3
	s_cbranch_vccnz .LBB0_19
	v_mul_f32_e32 v48, v3, v97
.LBB0_19:
	ds_write_b32 v46, v48 offset:792
	s_and_b64 vcc, exec, s[4:5]
	s_waitcnt vmcnt(27)
	v_mov_b32_e32 v48, v6
	s_cbranch_vccnz .LBB0_21
	v_mul_f32_e32 v48, v6, v98
.LBB0_21:
	ds_write_b32 v46, v48 offset:1056
	s_and_b64 vcc, exec, s[4:5]
	s_waitcnt vmcnt(26)
	v_mov_b32_e32 v48, v5
	s_cbranch_vccnz .LBB0_23
	v_mul_f32_e32 v48, v5, v99
.LBB0_23:
	ds_write_b32 v46, v48 offset:1320
	s_and_b64 vcc, exec, s[4:5]
	s_waitcnt vmcnt(25)
	v_mov_b32_e32 v48, v8
	s_cbranch_vccnz .LBB0_25
	v_mul_f32_e32 v48, v8, v100
.LBB0_25:
	ds_write_b32 v46, v48 offset:1584
	s_and_b64 vcc, exec, s[4:5]
	s_waitcnt vmcnt(24)
	v_mov_b32_e32 v48, v7
	s_cbranch_vccnz .LBB0_27
	v_mul_f32_e32 v48, v7, v101
.LBB0_27:
	ds_write_b32 v46, v48 offset:1848
	s_and_b64 vcc, exec, s[4:5]
	s_waitcnt vmcnt(23)
	v_mov_b32_e32 v48, v10
	s_cbranch_vccnz .LBB0_29
	v_mul_f32_e32 v48, v10, v102
.LBB0_29:
	ds_write_b32 v46, v48 offset:2112
	s_and_b64 vcc, exec, s[4:5]
	s_waitcnt vmcnt(22)
	v_mov_b32_e32 v48, v9
	s_cbranch_vccnz .LBB0_31
	v_mul_f32_e32 v48, v9, v103
.LBB0_31:
	ds_write_b32 v46, v48 offset:2376
	s_and_b64 vcc, exec, s[4:5]
	s_waitcnt vmcnt(21)
	v_mov_b32_e32 v48, v12
	s_cbranch_vccnz .LBB0_33
	v_mul_f32_e32 v48, v12, v104
; __device__ __forceinline__ void conv_matrix(const float* W, int K, int N, bf16* WT, const float* sk, const float* sn, int mode, LAS float* scr, int lane, int gw, int NGW) {
;     ...
;     for (; it < nitems; it += NGW) {
;         const int kb = it / nblk, nb = it - kb * nblk, n0 = 32 * nb, k0 = 64 * kb; int drow0 = n0;
;         if (mode == 1) drow0 = n0 < DFF ? 256 * (n0 >> 7) + (n0 & 127) : 256 * ((n0 - DFF) >> 7) + 128 + ((n0 - DFF) & 127);
; #pragma unroll
;         for (int i = 0; i < 32; ++i) { const int kk = 2 * i + (lane >> 5); float t = v[i]; if (sk) t *= sk[k0 + kk]; scr[kk * 33 + (lane & 31)] = t; }
.LBB0_33:
	ds_write_b32 v46, v48 offset:2640
	s_and_b64 vcc, exec, s[4:5]
	s_waitcnt vmcnt(20)
	v_mov_b32_e32 v48, v11
	s_cbranch_vccnz .LBB0_35
	v_mul_f32_e32 v48, v11, v105
.LBB0_35:
	ds_write_b32 v46, v48 offset:2904
	s_and_b64 vcc, exec, s[4:5]
	s_waitcnt vmcnt(19)
	v_mov_b32_e32 v48, v14
	s_cbranch_vccnz .LBB0_37
	v_mul_f32_e32 v48, v14, v106
.LBB0_37:
	ds_write_b32 v46, v48 offset:3168
	s_and_b64 vcc, exec, s[4:5]
	s_waitcnt vmcnt(18)
	v_mov_b32_e32 v48, v13
	s_cbranch_vccnz .LBB0_39
	v_mul_f32_e32 v48, v13, v107
.LBB0_39:
	ds_write_b32 v46, v48 offset:3432
	s_and_b64 vcc, exec, s[4:5]
	s_waitcnt vmcnt(17)
	v_mov_b32_e32 v48, v16
	s_cbranch_vccnz .LBB0_41
	v_mul_f32_e32 v48, v16, v108
.LBB0_41:
	ds_write_b32 v46, v48 offset:3696
	s_and_b64 vcc, exec, s[4:5]
	s_waitcnt vmcnt(16)
	v_mov_b32_e32 v48, v15
	s_cbranch_vccnz .LBB0_43
	v_mul_f32_e32 v48, v15, v109
.LBB0_43:
	ds_write_b32 v46, v48 offset:3960
	s_and_b64 vcc, exec, s[4:5]
	s_waitcnt vmcnt(15)
	v_mov_b32_e32 v48, v18
	s_cbranch_vccnz .LBB0_45
	v_mul_f32_e32 v48, v18, v110
.LBB0_45:
	ds_write_b32 v46, v48 offset:4224
	s_and_b64 vcc, exec, s[4:5]
	s_waitcnt vmcnt(14)
	v_mov_b32_e32 v48, v17
	s_cbranch_vccnz .LBB0_47
	v_mul_f32_e32 v48, v17, v111
.LBB0_47:
	ds_write_b32 v46, v48 offset:4488
	s_and_b64 vcc, exec, s[4:5]
	s_waitcnt vmcnt(13)
	v_mov_b32_e32 v48, v20
	s_cbranch_vccnz .LBB0_49
	v_mul_f32_e32 v48, v20, v112
.LBB0_49:
	ds_write_b32 v46, v48 offset:4752
	s_and_b64 vcc, exec, s[4:5]
	s_waitcnt vmcnt(12)
	v_mov_b32_e32 v48, v19
	s_cbranch_vccnz .LBB0_51
	v_mul_f32_e32 v48, v19, v113
.LBB0_51:
	ds_write_b32 v46, v48 offset:5016
	s_and_b64 vcc, exec, s[4:5]
	s_waitcnt vmcnt(11)
	v_mov_b32_e32 v48, v22
	s_cbranch_vccnz .LBB0_53
	v_mul_f32_e32 v48, v22, v114
.LBB0_53:
	ds_write_b32 v46, v48 offset:5280
	s_and_b64 vcc, exec, s[4:5]
	s_waitcnt vmcnt(10)
	v_mov_b32_e32 v48, v21
	s_cbranch_vccnz .LBB0_55
	v_mul_f32_e32 v48, v21, v115
.LBB0_55:
	ds_write_b32 v46, v48 offset:5544
	s_and_b64 vcc, exec, s[4:5]
	s_waitcnt vmcnt(9)
	v_mov_b32_e32 v48, v24
	s_cbranch_vccnz .LBB0_57
	v_mul_f32_e32 v48, v24, v116
.LBB0_57:
	ds_write_b32 v46, v48 offset:5808
	s_and_b64 vcc, exec, s[4:5]
	s_waitcnt vmcnt(8)
	v_mov_b32_e32 v48, v23
	s_cbranch_vccnz .LBB0_59
	v_mul_f32_e32 v48, v23, v117
.LBB0_59:
	ds_write_b32 v46, v48 offset:6072
	s_and_b64 vcc, exec, s[4:5]
	s_waitcnt vmcnt(7)
	v_mov_b32_e32 v48, v26
	s_cbranch_vccnz .LBB0_61
	v_mul_f32_e32 v48, v26, v118
.LBB0_61:
	ds_write_b32 v46, v48 offset:6336
	s_and_b64 vcc, exec, s[4:5]
	s_waitcnt vmcnt(6)
	v_mov_b32_e32 v48, v25
	s_cbranch_vccnz .LBB0_63
	v_mul_f32_e32 v48, v25, v119
.LBB0_63:
	ds_write_b32 v46, v48 offset:6600
	s_and_b64 vcc, exec, s[4:5]
	s_waitcnt vmcnt(5)
	v_mov_b32_e32 v48, v28
	s_cbranch_vccnz .LBB0_65
	v_mul_f32_e32 v48, v28, v120
.LBB0_65:
	ds_write_b32 v46, v48 offset:6864
	s_and_b64 vcc, exec, s[4:5]
	s_waitcnt vmcnt(4)
	v_mov_b32_e32 v48, v27
	s_cbranch_vccnz .LBB0_67
	v_mul_f32_e32 v48, v27, v121
.LBB0_67:
	ds_write_b32 v46, v48 offset:7128
	s_and_b64 vcc, exec, s[4:5]
	s_waitcnt vmcnt(3)
	v_mov_b32_e32 v48, v30
	s_cbranch_vccnz .LBB0_69
	v_mul_f32_e32 v48, v30, v122
.LBB0_69:
	ds_write_b32 v46, v48 offset:7392
	s_and_b64 vcc, exec, s[4:5]
	s_waitcnt vmcnt(2)
	v_mov_b32_e32 v48, v29
	s_cbranch_vccnz .LBB0_71
	v_mul_f32_e32 v48, v29, v123
.LBB0_71:
	ds_write_b32 v46, v48 offset:7656
	s_and_b64 vcc, exec, s[4:5]
	s_waitcnt vmcnt(1)
	v_mov_b32_e32 v48, v32
	s_cbranch_vccnz .LBB0_73
	v_mul_f32_e32 v48, v32, v124
.LBB0_73:
	ds_write_b32 v46, v48 offset:7920
	s_and_b64 vcc, exec, s[4:5]
	s_waitcnt vmcnt(0)
	v_mov_b32_e32 v48, v31
	s_cbranch_vccnz .LBB0_75
	v_mul_f32_e32 v48, v31, v125

; __device__ __forceinline__ void conv_matrix(const float* W, int K, int N, bf16* WT, const float* sk, const float* sn, int mode, LAS float* scr, int lane, int gw, int NGW) {
;     ...
;     for (; it < nitems; it += NGW) {
;         const int kb = it / nblk, nb = it - kb * nblk, n0 = 32 * nb, k0 = 64 * kb; int drow0 = n0;
;         if (mode == 1) drow0 = n0 < DFF ? 256 * (n0 >> 7) + (n0 & 127) : 256 * ((n0 - DFF) >> 7) + 128 + ((n0 - DFF) & 127);
; #pragma unroll
;         for (int i = 0; i < 32; ++i) { const int kk = 2 * i + (lane >> 5); float t = v[i]; if (sk) t *= sk[k0 + kk]; scr[kk * 33 + (lane & 31)] = t; }
.LBB0_310:
	v_cndmask_b32_e64 v43, 0, 1, s[0:1]
	s_lshl_b32 s6, s6, 6
	v_cmp_ne_u32_e64 s[4:5], 1, v43
	s_andn2_b64 vcc, exec, s[0:1]
	s_cbranch_vccnz .Lgn_skip_1
	s_ashr_i32 s7, s6, 31
	v_lshl_add_u64 v[216:217], s[6:7], 0, v[194:195]
	v_lshl_add_u64 v[216:217], v[216:217], 2, s[20:21]
	global_load_dword v218, v[216:217], off
	global_load_dword v219, v[216:217], off offset:8
	global_load_dword v220, v[216:217], off offset:16
	global_load_dword v221, v[216:217], off offset:24
	global_load_dword v223, v[216:217], off offset:32
	global_load_dword v224, v[216:217], off offset:40
	global_load_dword v225, v[216:217], off offset:48
	global_load_dword v226, v[216:217], off offset:56
	global_load_dword v227, v[216:217], off offset:64
	global_load_dword v228, v[216:217], off offset:72
	global_load_dword v229, v[216:217], off offset:80
	global_load_dword v230, v[216:217], off offset:88
	global_load_dword v231, v[216:217], off offset:96
	global_load_dword v232, v[216:217], off offset:104
	global_load_dword v233, v[216:217], off offset:112
	global_load_dword v234, v[216:217], off offset:120
	global_load_dword v235, v[216:217], off offset:128
	global_load_dword v236, v[216:217], off offset:136
	global_load_dword v237, v[216:217], off offset:144
	global_load_dword v238, v[216:217], off offset:152
	global_load_dword v239, v[216:217], off offset:160
	global_load_dword v240, v[216:217], off offset:168
	global_load_dword v241, v[216:217], off offset:176
	global_load_dword v242, v[216:217], off offset:184
	global_load_dword v243, v[216:217], off offset:192
	global_load_dword v244, v[216:217], off offset:200
	global_load_dword v245, v[216:217], off offset:208
	global_load_dword v247, v[216:217], off offset:216
	global_load_dword v248, v[216:217], off offset:224
	global_load_dword v249, v[216:217], off offset:232
	global_load_dword v250, v[216:217], off offset:240
	global_load_dword v251, v[216:217], off offset:248
.Lgn_skip_1:
	s_andn2_b64 vcc, exec, s[0:1]
	s_waitcnt vmcnt(31)
	v_mov_b32_e32 v43, v2
	s_cbranch_vccnz .LBB0_312
	v_mul_f32_e32 v43, v2, v218
.LBB0_312:
	ds_write_b32 v38, v43
	s_and_b64 vcc, exec, s[4:5]
	s_waitcnt vmcnt(30)
	v_mov_b32_e32 v43, v1
	s_cbranch_vccnz .LBB0_314
	v_mul_f32_e32 v43, v1, v219
.LBB0_314:
	ds_write_b32 v38, v43 offset:264
	s_and_b64 vcc, exec, s[4:5]
	s_waitcnt vmcnt(29)
	v_mov_b32_e32 v43, v4
	s_cbranch_vccnz .LBB0_316
	v_mul_f32_e32 v43, v4, v220
.LBB0_316:
	ds_write_b32 v38, v43 offset:528
	s_and_b64 vcc, exec, s[4:5]
	s_waitcnt vmcnt(28)
	v_mov_b32_e32 v43, v3
	s_cbranch_vccnz .LBB0_318
	v_mul_f32_e32 v43, v3, v221
.LBB0_318:
	ds_write_b32 v38, v43 offset:792
	s_and_b64 vcc, exec, s[4:5]
	s_waitcnt vmcnt(27)
	v_mov_b32_e32 v43, v6
	s_cbranch_vccnz .LBB0_320
	v_mul_f32_e32 v43, v6, v223
.LBB0_320:
	ds_write_b32 v38, v43 offset:1056
	s_and_b64 vcc, exec, s[4:5]
	s_waitcnt vmcnt(26)
	v_mov_b32_e32 v43, v5
	s_cbranch_vccnz .LBB0_322
	v_mul_f32_e32 v43, v5, v224
.LBB0_322:
	ds_write_b32 v38, v43 offset:1320
	s_and_b64 vcc, exec, s[4:5]
	s_waitcnt vmcnt(25)
	v_mov_b32_e32 v43, v8
	s_cbranch_vccnz .LBB0_324
	v_mul_f32_e32 v43, v8, v225
.LBB0_324:
	ds_write_b32 v38, v43 offset:1584
	s_and_b64 vcc, exec, s[4:5]
	s_waitcnt vmcnt(24)
	v_mov_b32_e32 v43, v7
	s_cbranch_vccnz .LBB0_326
	v_mul_f32_e32 v43, v7, v226
.LBB0_326:
	ds_write_b32 v38, v43 offset:1848
	s_and_b64 vcc, exec, s[4:5]
	s_waitcnt vmcnt(23)
	v_mov_b32_e32 v43, v10
	s_cbranch_vccnz .LBB0_328
	v_mul_f32_e32 v43, v10, v227
.LBB0_328:
	ds_write_b32 v38, v43 offset:2112
	s_and_b64 vcc, exec, s[4:5]
	s_waitcnt vmcnt(22)
	v_mov_b32_e32 v43, v9
	s_cbranch_vccnz .LBB0_330
	v_mul_f32_e32 v43, v9, v228
.LBB0_330:
	ds_write_b32 v38, v43 offset:2376
	s_and_b64 vcc, exec, s[4:5]
	s_waitcnt vmcnt(21)
	v_mov_b32_e32 v43, v12
	s_cbranch_vccnz .LBB0_332
	v_mul_f32_e32 v43, v12, v229
; __device__ __forceinline__ void conv_matrix(const float* W, int K, int N, bf16* WT, const float* sk, const float* sn, int mode, LAS float* scr, int lane, int gw, int NGW) {
;     ...
;     for (; it < nitems; it += NGW) {
;         const int kb = it / nblk, nb = it - kb * nblk, n0 = 32 * nb, k0 = 64 * kb; int drow0 = n0;
;         if (mode == 1) drow0 = n0 < DFF ? 256 * (n0 >> 7) + (n0 & 127) : 256 * ((n0 - DFF) >> 7) + 128 + ((n0 - DFF) & 127);
; #pragma unroll
;         for (int i = 0; i < 32; ++i) { const int kk = 2 * i + (lane >> 5); float t = v[i]; if (sk) t *= sk[k0 + kk]; scr[kk * 33 + (lane & 31)] = t; }
.LBB0_332:
	ds_write_b32 v38, v43 offset:2640
	s_and_b64 vcc, exec, s[4:5]
	s_waitcnt vmcnt(20)
	v_mov_b32_e32 v43, v11
	s_cbranch_vccnz .LBB0_334
	v_mul_f32_e32 v43, v11, v230
.LBB0_334:
	ds_write_b32 v38, v43 offset:2904
	s_and_b64 vcc, exec, s[4:5]
	s_waitcnt vmcnt(19)
	v_mov_b32_e32 v43, v14
	s_cbranch_vccnz .LBB0_336
	v_mul_f32_e32 v43, v14, v231
.LBB0_336:
	ds_write_b32 v38, v43 offset:3168
	s_and_b64 vcc, exec, s[4:5]
	s_waitcnt vmcnt(18)
	v_mov_b32_e32 v43, v13
	s_cbranch_vccnz .LBB0_338
	v_mul_f32_e32 v43, v13, v232
.LBB0_338:
	ds_write_b32 v38, v43 offset:3432
	s_and_b64 vcc, exec, s[4:5]
	s_waitcnt vmcnt(17)
	v_mov_b32_e32 v43, v16
	s_cbranch_vccnz .LBB0_340
	v_mul_f32_e32 v43, v16, v233
.LBB0_340:
	ds_write_b32 v38, v43 offset:3696
	s_and_b64 vcc, exec, s[4:5]
	s_waitcnt vmcnt(16)
	v_mov_b32_e32 v43, v15
	s_cbranch_vccnz .LBB0_342
	v_mul_f32_e32 v43, v15, v234
.LBB0_342:
	ds_write_b32 v38, v43 offset:3960
	s_and_b64 vcc, exec, s[4:5]
	s_waitcnt vmcnt(15)
	v_mov_b32_e32 v43, v18
	s_cbranch_vccnz .LBB0_344
	v_mul_f32_e32 v43, v18, v235
.LBB0_344:
	ds_write_b32 v38, v43 offset:4224
	s_and_b64 vcc, exec, s[4:5]
	s_waitcnt vmcnt(14)
	v_mov_b32_e32 v43, v17
	s_cbranch_vccnz .LBB0_346
	v_mul_f32_e32 v43, v17, v236
.LBB0_346:
	ds_write_b32 v38, v43 offset:4488
	s_and_b64 vcc, exec, s[4:5]
	s_waitcnt vmcnt(13)
	v_mov_b32_e32 v43, v20
	s_cbranch_vccnz .LBB0_348
	v_mul_f32_e32 v43, v20, v237
.LBB0_348:
	ds_write_b32 v38, v43 offset:4752
	s_and_b64 vcc, exec, s[4:5]
	s_waitcnt vmcnt(12)
	v_mov_b32_e32 v43, v19
	s_cbranch_vccnz .LBB0_350
	v_mul_f32_e32 v43, v19, v238
.LBB0_350:
	ds_write_b32 v38, v43 offset:5016
	s_and_b64 vcc, exec, s[4:5]
	s_waitcnt vmcnt(11)
	v_mov_b32_e32 v43, v22
	s_cbranch_vccnz .LBB0_352
	v_mul_f32_e32 v43, v22, v239
.LBB0_352:
	ds_write_b32 v38, v43 offset:5280
	s_and_b64 vcc, exec, s[4:5]
	s_waitcnt vmcnt(10)
	v_mov_b32_e32 v43, v21
	s_cbranch_vccnz .LBB0_354
	v_mul_f32_e32 v43, v21, v240
.LBB0_354:
	ds_write_b32 v38, v43 offset:5544
	s_and_b64 vcc, exec, s[4:5]
	s_waitcnt vmcnt(9)
	v_mov_b32_e32 v43, v24
	s_cbranch_vccnz .LBB0_356
	v_mul_f32_e32 v43, v24, v241
.LBB0_356:
	ds_write_b32 v38, v43 offset:5808
	s_and_b64 vcc, exec, s[4:5]
	s_waitcnt vmcnt(8)
	v_mov_b32_e32 v43, v23
	s_cbranch_vccnz .LBB0_358
	v_mul_f32_e32 v43, v23, v242
.LBB0_358:
	ds_write_b32 v38, v43 offset:6072
	s_and_b64 vcc, exec, s[4:5]
	s_waitcnt vmcnt(7)
	v_mov_b32_e32 v43, v26
	s_cbranch_vccnz .LBB0_360
	v_mul_f32_e32 v43, v26, v243
.LBB0_360:
	ds_write_b32 v38, v43 offset:6336
	s_and_b64 vcc, exec, s[4:5]
	s_waitcnt vmcnt(6)
	v_mov_b32_e32 v43, v25
	s_cbranch_vccnz .LBB0_362
	v_mul_f32_e32 v43, v25, v244
.LBB0_362:
	ds_write_b32 v38, v43 offset:6600
	s_and_b64 vcc, exec, s[4:5]
	s_waitcnt vmcnt(5)
	v_mov_b32_e32 v43, v28
	s_cbranch_vccnz .LBB0_364
	v_mul_f32_e32 v43, v28, v245
.LBB0_364:
	ds_write_b32 v38, v43 offset:6864
	s_and_b64 vcc, exec, s[4:5]
	s_waitcnt vmcnt(4)
	v_mov_b32_e32 v43, v27
	s_cbranch_vccnz .LBB0_366
	v_mul_f32_e32 v43, v27, v247
.LBB0_366:
	ds_write_b32 v38, v43 offset:7128
	s_and_b64 vcc, exec, s[4:5]
	s_waitcnt vmcnt(3)
	v_mov_b32_e32 v43, v30
	s_cbranch_vccnz .LBB0_368
	v_mul_f32_e32 v43, v30, v248
.LBB0_368:
	ds_write_b32 v38, v43 offset:7392
	s_and_b64 vcc, exec, s[4:5]
	s_waitcnt vmcnt(2)
	v_mov_b32_e32 v43, v29
	s_cbranch_vccnz .LBB0_370
	v_mul_f32_e32 v43, v29, v249
.LBB0_370:
	ds_write_b32 v38, v43 offset:7656
	s_and_b64 vcc, exec, s[4:5]
	s_waitcnt vmcnt(1)
	v_mov_b32_e32 v43, v32
	s_cbranch_vccnz .LBB0_372
	v_mul_f32_e32 v43, v32, v250
.LBB0_372:
	ds_write_b32 v38, v43 offset:7920
	s_and_b64 vcc, exec, s[4:5]
	s_waitcnt vmcnt(0)
	v_mov_b32_e32 v43, v31
	s_cbranch_vccnz .LBB0_374
	v_mul_f32_e32 v43, v31, v251
